# MLA loop: each wave issues the next tile's LDS writes in the middle of its softmax (before the PV MFMAs) instead of all waves writing at the end of the iteration
# baseline (speedup 1.0000x reference)
; DI void attn_mla128(KP P, char* lds, bool sample, int b, int h, int ublk) {
;     ...
;     auto load_tile = [&](int kt) {
; #pragma unroll
;         for (int i = 0; i < 2; ++i) { const int c = tid + i * 512;
;             rk[i] = *(const u32x4*)(Kp + (long)(kt * 128 + (c >> 3)) * 512 + (c & 7) * 8);
;             rv[i] = *(const u32x4*)(VT + (long)(c >> 4) * ldv + kt * 128 + (c & 15) * 8); }
;         rr = *(const u32x4*)(Kr + (long)(kt * 128 + (tid >> 2)) * 32 + (tid & 3) * 8);
;     };
;     ...
;     for (int it = 0; it < ntiles; ++it) {
;         const int kt = ntiles - 1 - it, cur = it & 1;
;         if (it + 1 < ntiles) load_tile(kt - 1);
;         if (wactive && kt * 128 < wmax) {
.LBB0_1221:
	s_mov_b32 s96, 0
	s_add_i32 s17, s12, 1
	s_cmp_lt_u32 s17, s9
	s_cselect_b64 s[6:7], -1, 0
	s_cmp_ge_u32 s17, s9
	s_cbranch_scc1 .LBB0_1227
	v_add_u32_e32 v0, s16, v158
	s_add_i32 s10, s16, 0x80
	v_ashrrev_i32_e32 v1, 31, v0
	v_lshlrev_b64 v[0:1], 10, v[0:1]
	s_ashr_i32 s11, s10, 31
	v_lshl_add_u64 v[0:1], v[156:157], 0, v[0:1]
	s_lshl_b64 s[10:11], s[10:11], 1
	global_load_dwordx4 v[120:123], v[0:1], off
	v_lshl_add_u64 v[0:1], v[150:151], 0, s[10:11]
	global_load_dwordx4 v[124:127], v[0:1], off offset:-256
	v_add_u32_e32 v0, s16, v159
	v_ashrrev_i32_e32 v1, 31, v0
	v_lshlrev_b64 v[0:1], 10, v[0:1]
	v_lshl_add_u64 v[0:1], v[156:157], 0, v[0:1]
	global_load_dwordx4 v[128:131], v[0:1], off
	v_lshl_add_u64 v[0:1], v[152:153], 0, s[10:11]
	global_load_dwordx4 v[132:135], v[0:1], off offset:-256
	v_add_u32_e32 v0, s16, v160
	v_ashrrev_i32_e32 v1, 31, v0
	v_lshlrev_b64 v[0:1], 6, v[0:1]
	v_lshl_add_u64 v[0:1], v[154:155], 0, v[0:1]
	global_load_dwordx4 v[136:139], v[0:1], off
	s_and_b32 s18, s12, 1
	s_and_saveexec_b64 s[10:11], s[2:3]
	s_cbranch_execnz .LBB0_1228

; DI void attn_mla128(KP P, char* lds, bool sample, int b, int h, int ublk) {
;     ...
;     auto store_tile = [&](int buf) {
;         char* kb_ = lds + buf * BUF; char* vb_ = kb_ + KBYTES;
; #pragma unroll
;         for (int i = 0; i < 2; ++i) { const int c = tid + i * 512;
;             *(u32x4*)(kb_ + (c >> 3) * KS + (c & 7) * 16) = rk[i];
;             *(u32x4*)(vb_ + (c >> 4) * VS + (c & 15) * 16) = rv[i]; }
;         *(u32x4*)(kb_ + (tid >> 2) * KS + 128 + (tid & 3) * 16) = rr;
;     };
;     ...
;         if (it + 1 < ntiles) store_tile(cur ^ 1);
;         __syncthreads();
.LBB0_1224:
	s_cmp_lg_u32 s96, 0
	s_cbranch_scc1 .LBB0_1225
	s_xor_b32 s6, s18, 1
	s_mul_i32 s6, s6, 0xac00
	s_add_i32 s6, s6, 0
	v_add3_u32 v0, s6, v163, v140
	s_waitcnt vmcnt(4)
	ds_write_b128 v0, v[120:123]
	v_add3_u32 v0, s6, v164, v248
	s_waitcnt vmcnt(3)
	ds_write2_b64 v0, v[124:125], v[126:127] offset1:2
	v_add3_u32 v0, s6, v166, v140
	s_waitcnt vmcnt(2)
	ds_write_b128 v0, v[128:131]
	v_add3_u32 v0, s6, v167, v248
	s_waitcnt vmcnt(1)
	ds_write2_b64 v0, v[132:133], v[134:135] offset1:2
	v_add3_u32 v0, s6, v165, v148
	s_waitcnt vmcnt(0)
	ds_write_b128 v0, v[136:139] offset:128

; DI void attn_mla128(KP P, char* lds, bool sample, int b, int h, int ublk) {
;     ...
;     auto store_tile = [&](int buf) {
;         char* kb_ = lds + buf * BUF; char* vb_ = kb_ + KBYTES;
; #pragma unroll
;         for (int i = 0; i < 2; ++i) { const int c = tid + i * 512;
;             *(u32x4*)(kb_ + (c >> 3) * KS + (c & 7) * 16) = rk[i];
;             *(u32x4*)(vb_ + (c >> 4) * VS + (c & 15) * 16) = rv[i]; }
;         *(u32x4*)(kb_ + (tid >> 2) * KS + 128 + (tid & 3) * 16) = rr;
;     };
;     ...
;             float mx = S[0][0];
; #pragma unroll
;             for (int blk = 0; blk < 4; ++blk)
; #pragma unroll
;                 for (int i = 0; i < 16; ++i) mx = fmaxf(mx, S[blk][i]);
;             mx = fmaxf(mx, __shfl_xor(mx, 32));
;             const float mnew = fmaxf(mrun, mx);
;             const float alpha = __builtin_amdgcn_exp2f(mrun - mnew);
;             mrun = mnew;
;             float ps = 0.f;
; #pragma unroll
;             for (int blk = 0; blk < 4; ++blk)
; #pragma unroll
;                 for (int i = 0; i < 16; ++i) { S[blk][i] = __builtin_amdgcn_exp2f(S[blk][i] - mnew); ps += S[blk][i]; }
;             lrun = lrun * alpha + ps;
.LBB0_1231:
	s_or_b64 exec, exec, s[14:15]
	v_max_f32_e32 v169, v81, v81
	v_max_f32_e32 v171, v80, v80
	v_max_f32_e32 v169, v171, v169
	v_max3_f32 v169, v169, v82, v83
	v_max3_f32 v169, v169, v84, v85
	v_max3_f32 v169, v169, v86, v87
	v_max3_f32 v169, v169, v88, v89
	v_max3_f32 v169, v169, v90, v91
	v_max3_f32 v169, v169, v92, v93
	v_max3_f32 v169, v169, v94, v95
	v_max3_f32 v169, v169, v64, v65
	v_max3_f32 v169, v169, v66, v67
	v_max3_f32 v169, v169, v68, v69
	v_max3_f32 v169, v169, v70, v71
	v_max3_f32 v169, v169, v72, v73
	v_max3_f32 v169, v169, v74, v75
	v_max3_f32 v169, v169, v76, v77
	v_max3_f32 v169, v169, v78, v79
	v_max3_f32 v169, v169, v16, v17
	v_max3_f32 v169, v169, v18, v19
	v_max3_f32 v169, v169, v20, v21
	v_max3_f32 v169, v169, v22, v23
	v_max3_f32 v169, v169, v24, v25
	v_max3_f32 v169, v169, v26, v27
	v_max3_f32 v169, v169, v28, v29
	v_max3_f32 v169, v169, v30, v31
	v_max3_f32 v169, v169, v0, v1
	v_max3_f32 v169, v169, v2, v3
	v_max3_f32 v169, v169, v4, v5
	v_max3_f32 v169, v169, v6, v7
	v_max3_f32 v169, v169, v8, v9
	v_max3_f32 v169, v169, v10, v11
	v_cmp_lt_i32_e32 vcc, v191, v184
	v_max3_f32 v169, v169, v12, v13
	v_max3_f32 v169, v169, v14, v15
	v_cndmask_b32_e32 v171, v183, v191, vcc
	v_lshlrev_b32_e32 v171, 2, v171
	ds_bpermute_b32 v171, v171, v169
	s_waitcnt lgkmcnt(0)
	v_max3_f32 v169, v170, v169, v171
	v_sub_f32_e32 v80, v80, v169
	v_exp_f32_e32 v171, v80
	v_sub_f32_e32 v81, v81, v169
	v_exp_f32_e32 v81, v81
	v_sub_f32_e32 v82, v82, v169
	v_exp_f32_e32 v82, v82
	v_sub_f32_e32 v83, v83, v169
	v_exp_f32_e32 v83, v83
	v_sub_f32_e32 v84, v84, v169
	v_sub_f32_e32 v80, v170, v169
	v_add_f32_e32 v170, 0, v171
	v_exp_f32_e32 v84, v84
	v_sub_f32_e32 v85, v85, v169
	v_add_f32_e32 v170, v81, v170
	v_exp_f32_e32 v85, v85
	v_sub_f32_e32 v86, v86, v169
	v_add_f32_e32 v170, v82, v170
	v_exp_f32_e32 v86, v86
	v_sub_f32_e32 v87, v87, v169
	v_add_f32_e32 v170, v83, v170
	v_exp_f32_e32 v87, v87
	v_sub_f32_e32 v88, v88, v169
	v_add_f32_e32 v170, v84, v170
	v_exp_f32_e32 v88, v88
	v_sub_f32_e32 v89, v89, v169
	v_add_f32_e32 v170, v85, v170
	v_exp_f32_e32 v89, v89
	v_sub_f32_e32 v90, v90, v169
	v_add_f32_e32 v170, v86, v170
	v_exp_f32_e32 v90, v90
	v_sub_f32_e32 v91, v91, v169
	v_add_f32_e32 v170, v87, v170
	v_exp_f32_e32 v91, v91
	v_sub_f32_e32 v92, v92, v169
	v_add_f32_e32 v170, v88, v170
	v_exp_f32_e32 v92, v92
	v_sub_f32_e32 v93, v93, v169
	v_add_f32_e32 v170, v89, v170
	v_exp_f32_e32 v93, v93
	v_sub_f32_e32 v94, v94, v169
	v_add_f32_e32 v170, v90, v170
	v_exp_f32_e32 v94, v94
	v_sub_f32_e32 v95, v95, v169
	v_add_f32_e32 v170, v91, v170
	v_exp_f32_e32 v95, v95
	v_sub_f32_e32 v64, v64, v169
	v_add_f32_e32 v170, v92, v170
	v_exp_f32_e32 v64, v64
	v_sub_f32_e32 v65, v65, v169
	v_add_f32_e32 v170, v93, v170
	v_exp_f32_e32 v65, v65
	v_sub_f32_e32 v66, v66, v169
	v_add_f32_e32 v170, v94, v170
	v_exp_f32_e32 v66, v66
	v_sub_f32_e32 v67, v67, v169
	v_add_f32_e32 v170, v95, v170
	v_exp_f32_e32 v67, v67
	v_sub_f32_e32 v68, v68, v169
	v_add_f32_e32 v170, v64, v170
	v_exp_f32_e32 v68, v68
	v_sub_f32_e32 v69, v69, v169
	v_add_f32_e32 v170, v65, v170
	v_exp_f32_e32 v69, v69
	v_sub_f32_e32 v70, v70, v169
	v_add_f32_e32 v170, v66, v170
	v_exp_f32_e32 v70, v70
	v_sub_f32_e32 v71, v71, v169
	v_add_f32_e32 v170, v67, v170
	v_exp_f32_e32 v71, v71
	v_sub_f32_e32 v72, v72, v169
	v_add_f32_e32 v170, v68, v170
	v_exp_f32_e32 v72, v72
	v_sub_f32_e32 v73, v73, v169
	v_add_f32_e32 v170, v69, v170
	v_exp_f32_e32 v73, v73
	v_sub_f32_e32 v74, v74, v169
	v_add_f32_e32 v170, v70, v170
	v_exp_f32_e32 v74, v74
	v_sub_f32_e32 v75, v75, v169
	v_add_f32_e32 v170, v71, v170
	v_exp_f32_e32 v75, v75
	v_sub_f32_e32 v76, v76, v169
	v_add_f32_e32 v170, v72, v170
	v_exp_f32_e32 v76, v76
	v_sub_f32_e32 v77, v77, v169
	v_add_f32_e32 v170, v73, v170
	v_exp_f32_e32 v77, v77
	v_sub_f32_e32 v78, v78, v169
	v_add_f32_e32 v170, v74, v170
	v_exp_f32_e32 v78, v78
	v_sub_f32_e32 v79, v79, v169
	v_add_f32_e32 v170, v75, v170
	v_exp_f32_e32 v79, v79
	v_sub_f32_e32 v16, v16, v169
	v_add_f32_e32 v170, v76, v170
	v_exp_f32_e32 v172, v16
	v_sub_f32_e32 v17, v17, v169
	v_add_f32_e32 v16, v77, v170
	v_exp_f32_e32 v170, v17
	v_sub_f32_e32 v17, v18, v169
	v_add_f32_e32 v16, v78, v16
	v_exp_f32_e32 v173, v17
	v_sub_f32_e32 v17, v19, v169
	v_add_f32_e32 v16, v79, v16
	v_exp_f32_e32 v174, v17
	v_sub_f32_e32 v17, v20, v169
	v_add_f32_e32 v16, v172, v16
	v_exp_f32_e32 v175, v17
	v_sub_f32_e32 v17, v21, v169
	v_add_f32_e32 v16, v170, v16
	v_exp_f32_e32 v202, v17
	v_sub_f32_e32 v17, v22, v169
	v_add_f32_e32 v16, v173, v16
	v_exp_f32_e32 v203, v17
	v_sub_f32_e32 v17, v23, v169
	v_add_f32_e32 v16, v174, v16
	v_exp_f32_e32 v204, v17
	v_sub_f32_e32 v17, v24, v169
	v_add_f32_e32 v16, v175, v16
	v_exp_f32_e32 v205, v17
	v_sub_f32_e32 v17, v25, v169
	v_add_f32_e32 v16, v202, v16
	v_exp_f32_e32 v206, v17
	v_sub_f32_e32 v17, v26, v169
	v_add_f32_e32 v16, v203, v16
	v_exp_f32_e32 v207, v17
	v_sub_f32_e32 v17, v27, v169
	v_add_f32_e32 v16, v204, v16
	v_exp_f32_e32 v208, v17
	v_sub_f32_e32 v17, v28, v169
	v_add_f32_e32 v16, v205, v16
	v_exp_f32_e32 v28, v17
	v_add_f32_e32 v16, v206, v16
	v_add_f32_e32 v16, v207, v16
	s_cmp_lg_u32 s6, 0
	s_cbranch_scc0 .Lmla_wskip
	s_mov_b64 s[100:101], exec
	s_mov_b64 exec, -1
	s_xor_b32 s97, s18, 1
	s_mul_i32 s97, s97, 0xac00
	s_add_i32 s97, s97, 0
	v_add3_u32 v224, s97, v163, v140
	s_waitcnt vmcnt(4)
	ds_write_b128 v224, v[120:123]
	v_add3_u32 v224, s97, v164, v248
	s_waitcnt vmcnt(3)
	ds_write2_b64 v224, v[124:125], v[126:127] offset1:2
	v_add3_u32 v224, s97, v166, v140
	s_waitcnt vmcnt(2)
	ds_write_b128 v224, v[128:131]
	v_add3_u32 v224, s97, v167, v248
	s_waitcnt vmcnt(1)
	ds_write2_b64 v224, v[132:133], v[134:135] offset1:2
	v_add3_u32 v224, s97, v165, v148
	s_waitcnt vmcnt(0)
	ds_write_b128 v224, v[136:139] offset:128
	s_mov_b64 exec, s[100:101]
	s_mov_b32 s96, 1
; DI unsigned pk2(float a, float b) { f32x2 f = {a, b}; bf2_t r = __builtin_convertvector(f, bf2_t); return __builtin_bit_cast(unsigned, r); }
; #define MFMA32(a, b, c) __builtin_amdgcn_mfma_f32_32x32x16_bf16((a), (b), (c), 0, 0, 0)
; DI void attn_mla128(KP P, char* lds, bool sample, int b, int h, int ublk) {
;     ...
;             float ps = 0.f;
; #pragma unroll
;             for (int blk = 0; blk < 4; ++blk)
; #pragma unroll
;                 for (int i = 0; i < 16; ++i) { S[blk][i] = __builtin_amdgcn_exp2f(S[blk][i] - mnew); ps += S[blk][i]; }
;             lrun = lrun * alpha + ps;
; #pragma unroll
;             for (int i = 0; i < 16; ++i) { O0[i] *= alpha; O1[i] *= alpha; }
; #pragma unroll
;             for (int blk = 0; blk < 4; ++blk)
; #pragma unroll
;                 for (int s = 0; s < 2; ++s) {
;                     u32x4 a;
;                     a.x = pk2(S[blk][8 * s], S[blk][8 * s + 1]); a.y = pk2(S[blk][8 * s + 2], S[blk][8 * s + 3]); a.z = pk2(S[blk][8 * s + 4], S[blk][8 * s + 5]); a.w = pk2(S[blk][8 * s + 6], S[blk][8 * s + 7]);
;                     const bf16x8 pf = __builtin_bit_cast(bf16x8, a);
;                     const int koff = (32 * blk + 16 * s + 4 * hh) * 2;
;                     const s16x4 lo0 = *(const s16x4*)(vb_ + ql * VS + koff), hi0 = *(const s16x4*)(vb_ + ql * VS + koff + 16);
;                     const s16x4 lo1 = *(const s16x4*)(vb_ + (32 + ql) * VS + koff), hi1 = *(const s16x4*)(vb_ + (32 + ql) * VS + koff + 16);
;                     const bf16x8 v0 = __builtin_shufflevector(lo0, hi0, 0, 1, 2, 3, 4, 5, 6, 7), v1 = __builtin_shufflevector(lo1, hi1, 0, 1, 2, 3, 4, 5, 6, 7);
;                     O0 = MFMA32(v0, pf, O0); O1 = MFMA32(v1, pf, O1);
;                 }
.Lmla_wskip:
	v_add3_u32 v24, s19, v161, v144
	v_add_f32_e32 v16, v208, v16
	v_add_u32_e32 v210, 0x6800, v24
	v_add_f32_e32 v209, v28, v16
	ds_read_b128 v[16:19], v210
	v_exp_f32_e32 v80, v80
	v_cvt_pk_bf16_f32 v20, v171, v81
	v_cvt_pk_bf16_f32 v21, v82, v83
	v_cvt_pk_bf16_f32 v22, v84, v85
	v_pk_mul_f32 v[46:47], v[46:47], v[80:81] op_sel_hi:[1,0]
	v_pk_mul_f32 v[44:45], v[44:45], v[80:81] op_sel_hi:[1,0]
	v_pk_mul_f32 v[42:43], v[42:43], v[80:81] op_sel_hi:[1,0]
	v_pk_mul_f32 v[40:41], v[40:41], v[80:81] op_sel_hi:[1,0]
	v_pk_mul_f32 v[38:39], v[38:39], v[80:81] op_sel_hi:[1,0]
	v_pk_mul_f32 v[36:37], v[36:37], v[80:81] op_sel_hi:[1,0]
	v_pk_mul_f32 v[34:35], v[34:35], v[80:81] op_sel_hi:[1,0]
	v_pk_mul_f32 v[32:33], v[32:33], v[80:81] op_sel_hi:[1,0]
	v_pk_mul_f32 v[62:63], v[62:63], v[80:81] op_sel_hi:[1,0]
	v_pk_mul_f32 v[60:61], v[60:61], v[80:81] op_sel_hi:[1,0]
	v_add_u32_e32 v81, 0x8800, v24
	ds_read_b128 v[24:27], v81 offset:512
	v_cvt_pk_bf16_f32 v23, v86, v87
	v_pk_mul_f32 v[58:59], v[58:59], v[80:81] op_sel_hi:[1,0]
	v_pk_mul_f32 v[56:57], v[56:57], v[80:81] op_sel_hi:[1,0]
	s_waitcnt lgkmcnt(1)
	v_mfma_f32_32x32x16_bf16 v[32:47], v[16:19], v[20:23], v[32:47]
	ds_read_b128 v[16:19], v210 offset:32
	v_mul_f32_e64 v54, v54, v80
	v_mul_f32_e64 v55, v55, v80
	v_mul_f32_e64 v52, v52, v80
	v_mul_f32_e64 v53, v53, v80
	v_pk_mul_f32 v[50:51], v[50:51], v[80:81] op_sel_hi:[1,0]
	v_pk_mul_f32 v[48:49], v[48:49], v[80:81] op_sel_hi:[1,0]
	v_sub_f32_e32 v0, v0, v169
	v_sub_f32_e32 v4, v4, v169
	s_waitcnt lgkmcnt(1)
	v_mfma_f32_32x32x16_bf16 v[48:63], v[24:27], v[20:23], v[48:63]
	v_sub_f32_e32 v20, v29, v169
	v_exp_f32_e32 v29, v20
	v_cvt_pk_bf16_f32 v20, v88, v89
	v_cvt_pk_bf16_f32 v21, v90, v91
	v_cvt_pk_bf16_f32 v22, v92, v93
	v_cvt_pk_bf16_f32 v23, v94, v95
	ds_read_b128 v[24:27], v81 offset:544
	v_sub_f32_e32 v8, v8, v169
	s_waitcnt lgkmcnt(1)
	v_mfma_f32_32x32x16_bf16 v[32:47], v[16:19], v[20:23], v[32:47]
	v_sub_f32_e32 v16, v30, v169
	v_exp_f32_e32 v30, v16
	v_add_f32_e32 v16, v29, v209
	v_sub_f32_e32 v17, v31, v169
	v_exp_f32_e32 v31, v17
	v_add_f32_e32 v82, v30, v16
	ds_read_b128 v[16:19], v210 offset:64
	s_waitcnt lgkmcnt(1)
	v_mfma_f32_32x32x16_bf16 v[48:63], v[24:27], v[20:23], v[48:63]
	v_cvt_pk_bf16_f32 v20, v64, v65
	v_exp_f32_e32 v64, v0
	v_sub_f32_e32 v0, v1, v169
	v_cvt_pk_bf16_f32 v21, v66, v67
	v_cvt_pk_bf16_f32 v22, v68, v69
	v_cvt_pk_bf16_f32 v23, v70, v71
	ds_read_b128 v[24:27], v81 offset:576
	v_exp_f32_e32 v65, v0
	v_sub_f32_e32 v0, v2, v169
	s_waitcnt lgkmcnt(1)
	v_mfma_f32_32x32x16_bf16 v[32:47], v[16:19], v[20:23], v[32:47]
	v_exp_f32_e32 v66, v0
	v_sub_f32_e32 v16, v3, v169
	ds_read_b128 v[0:3], v210 offset:96
	v_cvt_pk_bf16_f32 v17, v74, v75
	v_cvt_pk_bf16_f32 v18, v76, v77
	v_cvt_pk_bf16_f32 v19, v78, v79
	v_add_f32_e32 v82, v31, v82
	s_waitcnt lgkmcnt(1)
	v_mfma_f32_32x32x16_bf16 v[48:63], v[24:27], v[20:23], v[48:63]
	v_exp_f32_e32 v24, v16
	v_cvt_pk_bf16_f32 v16, v72, v73
	ds_read_b128 v[20:23], v81 offset:608
	v_exp_f32_e32 v25, v4
	v_sub_f32_e32 v4, v7, v169
	v_cvt_pk_bf16_f32 v7, v203, v204
	v_sub_f32_e32 v12, v12, v169
	s_waitcnt lgkmcnt(1)
	v_mfma_f32_32x32x16_bf16 v[32:47], v[0:3], v[16:19], v[32:47]
	v_sub_f32_e32 v0, v5, v169
	v_exp_f32_e32 v26, v0
	v_sub_f32_e32 v0, v6, v169
	v_exp_f32_e32 v27, v0
	ds_read_b128 v[0:3], v210 offset:128
	v_cvt_pk_bf16_f32 v5, v173, v174
	v_cvt_pk_bf16_f32 v6, v175, v202
	s_waitcnt lgkmcnt(1)
	v_mfma_f32_32x32x16_bf16 v[48:63], v[20:23], v[16:19], v[48:63]
	v_exp_f32_e32 v20, v4
	v_cvt_pk_bf16_f32 v4, v172, v170
	ds_read_b128 v[16:19], v81 offset:640
	v_exp_f32_e32 v21, v8
	v_sub_f32_e32 v8, v11, v169
	v_sub_f32_e32 v15, v15, v169
	v_exp_f32_e32 v12, v12
	s_waitcnt lgkmcnt(1)
	v_mfma_f32_32x32x16_bf16 v[32:47], v[0:3], v[4:7], v[32:47]
	v_sub_f32_e32 v0, v9, v169
	v_exp_f32_e32 v22, v0
	v_sub_f32_e32 v0, v10, v169
	v_exp_f32_e32 v23, v0
	ds_read_b128 v[0:3], v210 offset:160
	v_exp_f32_e32 v15, v15
	v_mov_b32_e32 v170, v169
	s_waitcnt lgkmcnt(1)
	v_mfma_f32_32x32x16_bf16 v[48:63], v[16:19], v[4:7], v[48:63]
	v_exp_f32_e32 v16, v8
	v_cvt_pk_bf16_f32 v4, v205, v206
	v_cvt_pk_bf16_f32 v5, v207, v208
	v_cvt_pk_bf16_f32 v6, v28, v29
	v_cvt_pk_bf16_f32 v7, v30, v31
	ds_read_b128 v[8:11], v81 offset:672
	v_add_f32_e32 v17, v64, v82
	s_waitcnt lgkmcnt(1)
	v_mfma_f32_32x32x16_bf16 v[32:47], v[0:3], v[4:7], v[32:47]
	v_sub_f32_e32 v0, v13, v169
	v_exp_f32_e32 v13, v0
	v_sub_f32_e32 v0, v14, v169
	v_exp_f32_e32 v14, v0
	ds_read_b128 v[0:3], v210 offset:192
	s_waitcnt lgkmcnt(1)
	v_mfma_f32_32x32x16_bf16 v[48:63], v[8:11], v[4:7], v[48:63]
	ds_read_b128 v[8:11], v81 offset:704
	v_cvt_pk_bf16_f32 v4, v64, v65
	v_cvt_pk_bf16_f32 v5, v66, v24
	v_cvt_pk_bf16_f32 v6, v25, v26
	v_cvt_pk_bf16_f32 v7, v27, v20
	s_waitcnt lgkmcnt(1)
	s_nop 0
	v_mfma_f32_32x32x16_bf16 v[32:47], v[0:3], v[4:7], v[32:47]
	v_add_f32_e32 v0, v65, v17
	v_add_f32_e32 v0, v66, v0
	v_add_f32_e32 v0, v24, v0
	v_add_f32_e32 v0, v25, v0
	v_add_f32_e32 v0, v26, v0
	v_add_f32_e32 v17, v27, v0
	ds_read_b128 v[0:3], v210 offset:224
	s_waitcnt lgkmcnt(1)
	v_mfma_f32_32x32x16_bf16 v[48:63], v[8:11], v[4:7], v[48:63]
	ds_read_b128 v[8:11], v81 offset:736
	v_add_f32_e32 v4, v20, v17
	v_add_f32_e32 v17, v21, v4
	v_cvt_pk_bf16_f32 v4, v21, v22
	v_cvt_pk_bf16_f32 v5, v23, v16
	v_cvt_pk_bf16_f32 v6, v12, v13
	v_cvt_pk_bf16_f32 v7, v14, v15
	s_waitcnt lgkmcnt(1)
	s_nop 0
	v_mfma_f32_32x32x16_bf16 v[32:47], v[0:3], v[4:7], v[32:47]
	v_add_f32_e32 v0, v22, v17
	v_add_f32_e32 v0, v23, v0
	v_add_f32_e32 v0, v16, v0
	v_add_f32_e32 v0, v12, v0
	v_add_f32_e32 v0, v13, v0
	v_add_f32_e32 v0, v14, v0
	v_add_f32_e32 v0, v15, v0
	s_waitcnt lgkmcnt(0)
	v_mfma_f32_32x32x16_bf16 v[48:63], v[8:11], v[4:7], v[48:63]
	v_fmac_f32_e32 v0, v149, v80
	v_mov_b32_e32 v149, v0

; __global__ void __launch_bounds__(NTHREADS) fwd_megakernel(Params Pval) {
	.amdhsa_kernel _Z14fwd_megakernel6Params
		.amdhsa_group_segment_fixed_size 0
		.amdhsa_private_segment_fixed_size 0
		.amdhsa_kernarg_size 1936
		.amdhsa_user_sgpr_count 2
		.amdhsa_user_sgpr_dispatch_ptr 0
		.amdhsa_user_sgpr_queue_ptr 0
		.amdhsa_user_sgpr_kernarg_segment_ptr 1
		.amdhsa_user_sgpr_dispatch_id 0
		.amdhsa_user_sgpr_kernarg_preload_length 0
		.amdhsa_user_sgpr_kernarg_preload_offset 0
		.amdhsa_user_sgpr_private_segment_size 0
		.amdhsa_uses_dynamic_stack 0
		.amdhsa_enable_private_segment 0
		.amdhsa_system_sgpr_workgroup_id_x 1
		.amdhsa_system_sgpr_workgroup_id_y 0
		.amdhsa_system_sgpr_workgroup_id_z 0
		.amdhsa_system_sgpr_workgroup_info 0
		.amdhsa_system_vgpr_workitem_id 2
		.amdhsa_next_free_vgpr 252
		.amdhsa_next_free_sgpr 102
		.amdhsa_accum_offset 252
		.amdhsa_reserve_vcc 1
		.amdhsa_float_round_mode_32 0
		.amdhsa_float_round_mode_16_64 0
		.amdhsa_float_denorm_mode_32 3
		.amdhsa_float_denorm_mode_16_64 3
		.amdhsa_dx10_clamp 1
		.amdhsa_ieee_mode 1
		.amdhsa_fp16_overflow 0
		.amdhsa_tg_split 0
		.amdhsa_exception_fp_ieee_invalid_op 0
		.amdhsa_exception_fp_denorm_src 0
		.amdhsa_exception_fp_ieee_div_zero 0
		.amdhsa_exception_fp_ieee_overflow 0
		.amdhsa_exception_fp_ieee_underflow 0
		.amdhsa_exception_fp_ieee_inexact 0
		.amdhsa_exception_int_div_zero 0
	.end_amdhsa_kernel

; __global__ void __launch_bounds__(NTHREADS) fwd_megakernel(Params Pval) {
amdhsa.kernels:
  - .agpr_count:     0
    .args:
      - .offset:         0
        .size:           1680
        .value_kind:     by_value
      - .offset:         1680
        .size:           4
        .value_kind:     hidden_block_count_x
      - .offset:         1684
        .size:           4
        .value_kind:     hidden_block_count_y
      - .offset:         1688
        .size:           4
        .value_kind:     hidden_block_count_z
      - .offset:         1692
        .size:           2
        .value_kind:     hidden_group_size_x
      - .offset:         1694
        .size:           2
        .value_kind:     hidden_group_size_y
      - .offset:         1696
        .size:           2
        .value_kind:     hidden_group_size_z
      - .offset:         1698
        .size:           2
        .value_kind:     hidden_remainder_x
      - .offset:         1700
        .size:           2
        .value_kind:     hidden_remainder_y
      - .offset:         1702
        .size:           2
        .value_kind:     hidden_remainder_z
      - .offset:         1720
        .size:           8
        .value_kind:     hidden_global_offset_x
      - .offset:         1728
        .size:           8
        .value_kind:     hidden_global_offset_y
      - .offset:         1736
        .size:           8
        .value_kind:     hidden_global_offset_z
      - .offset:         1744
        .size:           2
        .value_kind:     hidden_grid_dims
      - .offset:         1768
        .size:           8
        .value_kind:     hidden_multigrid_sync_arg
      - .offset:         1800
        .size:           4
        .value_kind:     hidden_dynamic_lds_size
    .group_segment_fixed_size: 0
    .kernarg_segment_align: 8
    .kernarg_segment_size: 1936
    .language:       OpenCL C
    .language_version:
      - 2
      - 0
    .max_flat_workgroup_size: 512
    .name:           _Z14fwd_megakernel6Params
    .private_segment_fixed_size: 0
    .sgpr_count:     108
    .sgpr_spill_count: 57
    .symbol:         _Z14fwd_megakernel6Params.kd
    .uniform_work_group_size: 1
    .uses_dynamic_stack: false
    .vgpr_count:     252
    .vgpr_spill_count: 0
    .wavefront_size: 64
